# phase chaining T0: K-GEMM last K-loop iteration prefetches V0's first LDS stages; K drain + V0 prologue removed
# baseline (speedup 1.0000x reference)
.LBB0_588:
	s_ashr_i32 s25, s24, 31
	s_lshl_b64 s[30:31], s[24:25], 19
	s_add_u32 s30, s64, s30
	s_addc_u32 s31, s65, s31
	s_and_b64 s[34:35], s[0:1], exec
	s_cselect_b32 s25, s31, s45
	s_cselect_b32 s50, s30, s44
	s_ashr_i32 s19, s18, 31
	s_lshl_b64 s[34:35], s[18:19], 19
	v_readlane_b32 s2, v252, 22
	v_readlane_b32 s3, v252, 23
	s_add_u32 s34, s2, s34
	s_addc_u32 s35, s3, s35
	s_and_b64 s[52:53], s[0:1], exec
	s_cselect_b32 s19, s35, s47
	s_cselect_b32 s51, s34, s46
	s_cbranch_scc1 .Lch_t0_hn
	s_lshr_b32 s2, s85, 3
	s_and_b32 s2, s2, 3
	s_lshl_b32 s2, s2, 19
	s_add_u32 s50, s42, 0xc600000
	s_addc_u32 s25, s43, 0
	s_add_u32 s50, s50, s2
	s_addc_u32 s25, s25, 0
	s_and_b32 s2, s85, 7
	s_lshl_b32 s2, s2, 3
	s_lshr_b32 s3, s85, 5
	s_add_i32 s2, s2, s3
	s_lshl_b32 s3, s2, 19
	s_add_u32 s51, s64, s3
	s_addc_u32 s19, s65, 0
.Lch_t0_hn:
	s_add_u32 s44, s44, 0x40080
	s_addc_u32 s45, s45, 0
	s_add_u32 s52, s46, 0x100
	v_mov_b32_e32 v0, 0
	s_addc_u32 s53, s47, 0
	s_mov_b32 s54, -2
	v_mov_b32_e32 v1, v0
	v_mov_b32_e32 v2, v0
	v_mov_b32_e32 v3, v0
	v_mov_b32_e32 v4, v0
	v_mov_b32_e32 v5, v0
	v_mov_b32_e32 v6, v0
	v_mov_b32_e32 v7, v0
	v_mov_b32_e32 v8, v0
	v_mov_b32_e32 v9, v0
	v_mov_b32_e32 v10, v0
	v_mov_b32_e32 v11, v0
	v_mov_b32_e32 v16, v0
	v_mov_b32_e32 v17, v0
	v_mov_b32_e32 v18, v0
	v_mov_b32_e32 v19, v0
	v_mov_b32_e32 v24, v0
	v_mov_b32_e32 v25, v0
	v_mov_b32_e32 v26, v0
	v_mov_b32_e32 v27, v0
	v_mov_b32_e32 v32, v0
	v_mov_b32_e32 v33, v0
	v_mov_b32_e32 v34, v0
	v_mov_b32_e32 v35, v0
	v_mov_b32_e32 v40, v0
	v_mov_b32_e32 v41, v0
	v_mov_b32_e32 v42, v0
	v_mov_b32_e32 v43, v0
	v_mov_b32_e32 v48, v0
	v_mov_b32_e32 v49, v0
	v_mov_b32_e32 v50, v0
	v_mov_b32_e32 v51, v0
	v_mov_b32_e32 v12, v0
	v_mov_b32_e32 v13, v0
	v_mov_b32_e32 v14, v0
	v_mov_b32_e32 v15, v0
	v_mov_b32_e32 v20, v0
	v_mov_b32_e32 v21, v0
	v_mov_b32_e32 v22, v0
	v_mov_b32_e32 v23, v0
	v_mov_b32_e32 v28, v0
	v_mov_b32_e32 v29, v0
	v_mov_b32_e32 v30, v0
	v_mov_b32_e32 v31, v0
	v_mov_b32_e32 v36, v0
	v_mov_b32_e32 v37, v0
	v_mov_b32_e32 v38, v0
	v_mov_b32_e32 v39, v0
	v_mov_b32_e32 v44, v0
	v_mov_b32_e32 v45, v0
	v_mov_b32_e32 v46, v0
	v_mov_b32_e32 v47, v0
	v_mov_b32_e32 v52, v0
	v_mov_b32_e32 v53, v0
	v_mov_b32_e32 v54, v0
	v_mov_b32_e32 v55, v0
	v_mov_b32_e32 v56, v0
	v_mov_b32_e32 v57, v0
	v_mov_b32_e32 v58, v0
	v_mov_b32_e32 v59, v0
	v_mov_b32_e32 v60, v0
	v_mov_b32_e32 v61, v0
	v_mov_b32_e32 v62, v0
	v_mov_b32_e32 v63, v0
	v_mov_b32_e32 v64, v0
	v_mov_b32_e32 v65, v0
	v_mov_b32_e32 v66, v0
	v_mov_b32_e32 v67, v0
	v_mov_b32_e32 v68, v0
	v_mov_b32_e32 v69, v0
	v_mov_b32_e32 v70, v0
	v_mov_b32_e32 v71, v0
	v_mov_b32_e32 v72, v0
	v_mov_b32_e32 v73, v0
	v_mov_b32_e32 v74, v0
	v_mov_b32_e32 v75, v0
	v_mov_b32_e32 v80, v0
	v_mov_b32_e32 v81, v0
	v_mov_b32_e32 v82, v0
	v_mov_b32_e32 v83, v0
	v_mov_b32_e32 v88, v0
	v_mov_b32_e32 v89, v0
	v_mov_b32_e32 v90, v0
	v_mov_b32_e32 v91, v0
	v_mov_b32_e32 v96, v0
	v_mov_b32_e32 v97, v0
	v_mov_b32_e32 v98, v0
	v_mov_b32_e32 v99, v0
	v_mov_b32_e32 v104, v0
	v_mov_b32_e32 v105, v0
	v_mov_b32_e32 v106, v0
	v_mov_b32_e32 v107, v0
	v_mov_b32_e32 v112, v0
	v_mov_b32_e32 v113, v0
	v_mov_b32_e32 v114, v0
	v_mov_b32_e32 v115, v0
	v_mov_b32_e32 v76, v0
	v_mov_b32_e32 v77, v0
	v_mov_b32_e32 v78, v0
	v_mov_b32_e32 v79, v0
	v_mov_b32_e32 v84, v0
	v_mov_b32_e32 v85, v0
	v_mov_b32_e32 v86, v0
	v_mov_b32_e32 v87, v0
	v_mov_b32_e32 v92, v0
	v_mov_b32_e32 v93, v0
	v_mov_b32_e32 v94, v0
	v_mov_b32_e32 v95, v0
	v_mov_b32_e32 v100, v0
	v_mov_b32_e32 v101, v0
	v_mov_b32_e32 v102, v0
	v_mov_b32_e32 v103, v0
	v_mov_b32_e32 v108, v0
	v_mov_b32_e32 v109, v0
	v_mov_b32_e32 v110, v0
	v_mov_b32_e32 v111, v0
	v_mov_b32_e32 v116, v0
	v_mov_b32_e32 v117, v0
	v_mov_b32_e32 v118, v0
	v_mov_b32_e32 v119, v0
	v_mov_b32_e32 v120, v0
	v_mov_b32_e32 v121, v0
	v_mov_b32_e32 v122, v0
	v_mov_b32_e32 v123, v0
	v_mov_b32_e32 v124, v0
	v_mov_b32_e32 v125, v0
	v_mov_b32_e32 v126, v0
	v_mov_b32_e32 v127, v0

.LBB0_595:
	s_andn2_b64 vcc, exec, s[4:5]
	s_cbranch_vccnz .Lch_t0_nb
	s_barrier
.Lch_t0_nb:
.LBB0_596:
	s_add_u32 s0, s42, 0x6000000
	s_addc_u32 s1, s43, 0
	v_writelane_b32 v253, s0, 26
	v_cndmask_b32_e64 v0, 0, 1, s[22:23]
	v_mov_b32_e32 v15, v170
	v_writelane_b32 v253, s1, 27
	v_cmp_ne_u32_e64 s[0:1], 1, v0
	s_andn2_b64 vcc, exec, s[22:23]
	v_readfirstlane_b32 s2, v15
	v_writelane_b32 v253, s0, 28
	s_nop 1
	v_writelane_b32 v253, s1, 29
	s_cbranch_vccnz .LBB0_616
	v_lshlrev_b32_e32 v0, 4, v15
	v_add_u32_e32 v1, 0x2000, v0
	v_ashrrev_i32_e32 v2, 31, v1
	v_lshrrev_b32_e32 v2, 22, v2
	v_add_u32_e32 v2, v1, v2
	v_ashrrev_i32_e32 v12, 10, v2
	v_mul_i32_i24_e32 v2, 0x400, v12
	v_sub_u32_e32 v1, v1, v2
	v_lshrrev_b32_e32 v2, 4, v1
	v_bitop3_b32 v1, v2, v1, 32 bitop3:0x6c
	v_ashrrev_i32_e32 v2, 31, v1
	v_lshrrev_b32_e32 v2, 26, v2
	v_add_u32_e32 v2, v1, v2
	v_lshlrev_b32_e32 v3, 3, v12
	v_ashrrev_i32_e32 v13, 6, v2
	v_and_b32_e32 v3, -16, v3
	v_add_u32_e32 v3, v13, v3
	v_and_b32_e32 v4, 3, v13
	s_mov_b32 s0, 0x1fffe0
	v_lshrrev_b32_e32 v5, 2, v3
	v_lshlrev_b32_e32 v6, 1, v3
	v_and_b32_e32 v2, 0xc0, v2
	v_and_or_b32 v4, v3, s0, v4
	v_and_b32_e32 v5, 4, v5
	v_and_b32_e32 v6, 24, v6
	v_sub_u32_e32 v1, v1, v2
	v_mov_b32_e32 v2, 1
	v_or3_b32 v4, v4, v5, v6
	v_lshlrev_b32_e32 v5, 5, v12
	v_ashrrev_i16_sdwa v1, v2, sext(v1) dst_sel:DWORD dst_unused:UNUSED_PAD src0_sel:DWORD src1_sel:BYTE_0
	v_and_b32_e32 v5, 32, v5
	v_bfe_i32 v14, v1, 0, 16
	v_add_lshl_u32 v1, v5, v14, 1
	v_lshl_add_u32 v128, v4, 11, v1
	v_lshl_add_u32 v132, v3, 11, v1
	v_bfe_i32 v1, v15, 27, 1
	v_lshrrev_b32_e32 v1, 22, v1
	v_add_u32_e32 v1, v0, v1
	v_and_b32_e32 v1, 0xfffffc00, v1
	v_sub_u32_e32 v0, v0, v1
	v_lshrrev_b32_e32 v1, 4, v0
	v_bitop3_b32 v1, v1, v0, 32 bitop3:0x6c
	v_ashrrev_i32_e32 v0, 31, v0
	v_lshrrev_b32_e32 v0, 26, v0
	v_add_u32_e32 v0, v1, v0
	v_ashrrev_i32_e32 v16, 6, v0
	v_ashrrev_i32_e32 v0, 31, v15
	v_lshrrev_b32_e32 v0, 26, v0
	v_add_u32_e32 v0, v15, v0
	v_ashrrev_i32_e32 v17, 6, v0
	v_lshlrev_b32_e32 v0, 3, v17
	v_and_b32_e32 v0, -16, v0
	s_add_u32 s12, s42, 0xc600000
	v_add_u32_e32 v0, v16, v0
	v_and_b32_e32 v3, 3, v16
	s_addc_u32 s13, s43, 0
	v_and_or_b32 v3, v0, s0, v3
	s_lshr_b32 s0, s67, 24
	s_add_i32 s0, s62, s0
	s_ashr_i32 s1, s0, 8
	s_and_b32 s0, s0, 0xff00
	s_sub_i32 s0, s62, s0
	s_sext_i32_i16 s3, s0
	s_bfe_u32 s3, s3, 0x2001d
	s_add_i32 s3, s0, s3
	s_sext_i32_i16 s4, s3
	s_and_b32 s3, s3, 0xfffc
	v_lshrrev_b32_e32 v4, 2, v0
	v_lshlrev_b32_e32 v5, 1, v0
	s_sub_i32 s0, s0, s3
	v_and_b32_e32 v4, 4, v4
	v_and_b32_e32 v5, 24, v5
	s_lshl_b32 s1, s1, 2
	s_sext_i32_i16 s0, s0
	s_ashr_i32 s5, s2, 6
	v_or3_b32 v3, v3, v4, v5
	v_mul_i32_i24_e32 v5, 64, v16
	s_lshr_b32 s4, s4, 2
	s_add_i32 s0, s1, s0
	v_sub_u32_e32 v1, v1, v5
	s_ashr_i32 s1, s0, 31
	s_bfe_i64 s[8:9], s[4:5], 0x100000
	s_ashr_i32 s21, s2, 8
	s_lshl_b32 s14, s5, 10
	v_lshlrev_b32_e32 v4, 5, v17
	v_ashrrev_i16_sdwa v1, v2, sext(v1) dst_sel:DWORD dst_unused:UNUSED_PAD src0_sel:DWORD src1_sel:BYTE_0
	s_lshl_b64 s[6:7], s[0:1], 19
	s_lshl_b64 s[8:9], s[8:9], 19
	v_and_b32_e32 v4, 32, v4
	v_bfe_i32 v18, v1, 0, 16
	s_add_u32 s46, s64, s8
	v_add_lshl_u32 v1, v4, v18, 1
	s_addc_u32 s47, s65, s9
	s_add_i32 s15, s14, 0
	v_lshl_add_u32 v134, v3, 11, v1
	s_add_i32 m0, s15, 0x10000
	v_add_u32_e32 v136, 0x40000, v134
	s_add_i32 m0, s15, 0x12000
	v_add_u32_e32 v130, 0x40000, v128
	s_add_i32 m0, s15, 0x14000
	v_lshl_add_u32 v138, v0, 11, v1
	s_add_i32 m0, s15, 0x16000
	s_add_u32 s44, s12, s6
	s_addc_u32 s45, s13, s7
	s_add_i32 s16, s15, 0x2000
	s_mov_b32 m0, s15
	s_add_u32 s6, s44, 0x40000
	s_mov_b32 m0, s16
	s_addc_u32 s7, s45, 0
	s_add_i32 s17, s15, 0x4000
	s_mov_b32 m0, s17
	s_add_i32 s18, s15, 0x6000
	s_mov_b32 m0, s18
	v_mov_b32_e32 v141, 0
	v_mov_b32_e32 v135, v141
	v_mov_b32_e32 v129, v141
	v_mov_b32_e32 v137, v141
	v_mov_b32_e32 v131, v141
	v_mov_b32_e32 v139, v141
	v_mov_b32_e32 v133, v141
	s_cmp_eq_u32 s21, 1
	s_mov_b32 s1, 0
	v_lshl_add_u64 v[6:7], s[46:47], 0, v[134:135]
	v_lshl_add_u64 v[4:5], s[46:47], 0, v[128:129]
	v_lshl_add_u64 v[2:3], s[46:47], 0, v[136:137]
	v_lshl_add_u64 v[0:1], s[46:47], 0, v[130:131]
	v_lshl_add_u64 v[8:9], s[44:45], 0, v[138:139]
	s_cselect_b64 s[6:7], -1, 0
	s_cmp_lg_u32 s21, 1
	v_lshl_add_u64 v[10:11], s[44:45], 0, v[132:133]
	s_cbranch_scc1 .LBB0_599
.LBB0_599:
	s_mov_b64 s[8:9], 0x80
	s_add_i32 m0, s15, 0x18000
	v_lshl_add_u64 v[6:7], v[6:7], 0, s[8:9]
	v_lshl_add_u64 v[4:5], v[4:5], 0, s[8:9]
	s_add_i32 m0, s15, 0x1a000
	s_add_i32 s19, s15, 0x8000
	v_lshl_add_u64 v[4:5], v[8:9], 0, s[8:9]
	s_mov_b32 m0, s19
	s_add_i32 s20, s15, 0xa000
	v_lshl_add_u64 v[4:5], v[10:11], 0, s[8:9]
	s_mov_b32 m0, s20
	v_lshl_add_u64 v[2:3], v[2:3], 0, s[8:9]
	s_add_i32 m0, s15, 0x1c000
	v_lshl_add_u64 v[0:1], v[0:1], 0, s[8:9]
	s_add_i32 m0, s15, 0x1e000
	s_lshl_b32 s3, s21, 13
	v_lshrrev_b32_e32 v1, 1, v15
	v_and_b32_e32 v1, 24, v1
	v_and_b32_e32 v0, 15, v15
	v_lshlrev_b32_e32 v2, 1, v1
	v_lshl_or_b32 v150, s21, 6, v0
	v_lshl_or_b32 v0, v0, 6, v2
	v_lshlrev_b32_e32 v2, 2, v15
	v_and_b32_e32 v2, 32, v2
	v_bitop3_b32 v3, v0, s3, v2 bitop3:0xde
	s_lshl_b32 s3, s5, 5
	s_and_b32 s3, s3, 0x60
	s_sext_i32_i16 s48, s4
	s_lshl_b32 s4, s3, 7
	v_bitop3_b32 v151, v0, s4, v2 bitop3:0xde
	v_or_b32_e32 v0, s3, v1
	v_lshlrev_b32_e32 v1, 14, v17
	v_and_b32_e32 v1, 0xffff8000, v1
	v_lshl_add_u32 v1, v16, 11, v1
	v_and_b32_e32 v2, 1, v17
	v_lshl_or_b32 v1, v2, 6, v1
	v_lshl_add_u32 v142, v18, 1, v1
	v_lshlrev_b32_e32 v1, 14, v12
	v_and_b32_e32 v1, 0xffff8000, v1
	s_cmpk_lt_u32 s2, 0x100
	v_lshl_add_u32 v1, v13, 11, v1
	v_and_b32_e32 v2, 1, v12
	s_cselect_b64 s[22:23], -1, 0
	v_lshl_or_b32 v1, v2, 6, v1
	s_add_i32 s21, 0, 0x10000
	s_add_i32 s28, 0, 0x14000
	v_mov_b32_e32 v143, v141
	v_lshl_add_u32 v144, v14, 1, v1
	v_mov_b32_e32 v145, v141
	v_mov_b64_e32 v[146:147], 0x100
	v_mov_b64_e32 v[148:149], 0xff
	v_add_u32_e32 v152, s21, v151
	v_add_u32_e32 v153, s28, v151
	v_add_u32_e32 v154, 0, v3
	v_lshlrev_b32_e32 v140, 1, v0
	s_mov_b32 s29, 0
	s_branch .LBB0_602
